# XCD barrier: the last arriver of an XCD issues its acquire invalidate together with the L2 write-back instead of after the release
# baseline (speedup 1.0000x reference)
.LBB0_70:
	s_andn2_saveexec_b64 s[8:9], s[8:9]
	s_cbranch_execz .LBB0_90
	s_mov_b64 s[8:9], exec
	buffer_wbl2 sc1
	buffer_inv sc1
	s_waitcnt lgkmcnt(0)
	s_waitcnt vmcnt(0)
	v_mbcnt_lo_u32_b32 v1, s8, 0
	v_mbcnt_hi_u32_b32 v1, s9, v1
	v_cmp_eq_u32_e32 vcc, 0, v1
	s_and_saveexec_b64 s[10:11], vcc
	s_cbranch_execz .LBB0_73
	s_bcnt1_i32_b64 s3, s[8:9]
	v_mov_b32_e32 v2, 0x11083000
	v_mov_b32_e32 v3, s3
	global_atomic_add v2, v2, v3, s[4:5] offset:1024 sc0

.LBB0_87:
	s_or_b64 exec, exec, s[4:5]
	s_mov_b64 s[4:5], exec
	v_mbcnt_lo_u32_b32 v0, s4, 0
	v_mbcnt_hi_u32_b32 v0, s5, v0
	v_cmp_eq_u32_e32 vcc, 0, v0
	s_waitcnt vmcnt(0)
	s_and_saveexec_b64 s[8:9], vcc
	s_cbranch_execz .LBB0_89
	s_bcnt1_i32_b64 s3, s[4:5]
	v_mov_b32_e32 v0, 0x2000
	v_mov_b32_e32 v1, s3
.LBB0_89:
	s_or_b64 exec, exec, s[8:9]
	s_waitcnt vmcnt(0)

.LBB0_229:
	s_andn2_saveexec_b64 s[8:9], s[8:9]
	s_cbranch_execz .LBB0_249
	s_mov_b64 s[8:9], exec
	buffer_wbl2 sc1
	s_waitcnt lgkmcnt(0)
	buffer_inv sc1
	s_waitcnt vmcnt(0)
	v_mbcnt_lo_u32_b32 v1, s8, 0
	v_mbcnt_hi_u32_b32 v1, s9, v1
	v_cmp_eq_u32_e32 vcc, 0, v1
	s_and_saveexec_b64 s[10:11], vcc
	s_cbranch_execz .LBB0_232
	s_bcnt1_i32_b64 s3, s[8:9]
	v_mov_b32_e32 v2, 0x11083000
	v_mov_b32_e32 v3, s3
	global_atomic_add v2, v2, v3, s[4:5] offset:1024 sc0

.LBB0_246:
	s_or_b64 exec, exec, s[4:5]
	s_mov_b64 s[4:5], exec
	v_mbcnt_lo_u32_b32 v0, s4, 0
	v_mbcnt_hi_u32_b32 v0, s5, v0
	v_cmp_eq_u32_e32 vcc, 0, v0
	s_waitcnt vmcnt(0)
	s_and_saveexec_b64 s[8:9], vcc
	s_cbranch_execz .LBB0_248
	s_bcnt1_i32_b64 s3, s[4:5]
	v_mov_b32_e32 v0, 0x2000
	v_mov_b32_e32 v1, s3
.LBB0_248:
	s_or_b64 exec, exec, s[8:9]
	s_waitcnt vmcnt(0)

.LBB0_301:
	s_or_b64 exec, exec, s[4:5]
	s_mov_b64 s[4:5], exec
	v_mbcnt_lo_u32_b32 v0, s4, 0
	v_mbcnt_hi_u32_b32 v0, s5, v0
	v_cmp_eq_u32_e32 vcc, 0, v0
	s_waitcnt vmcnt(0)
	s_and_saveexec_b64 s[8:9], vcc
	s_cbranch_execz .LBB0_303
	s_bcnt1_i32_b64 s3, s[4:5]
	v_mov_b32_e32 v0, 0x2000
	v_mov_b32_e32 v1, s3
.LBB0_303:
	s_or_b64 exec, exec, s[8:9]
	s_waitcnt vmcnt(0)

.LBB0_391:
	s_andn2_saveexec_b64 s[8:9], s[8:9]
	s_cbranch_execz .LBB0_411
	s_mov_b64 s[8:9], exec
	buffer_wbl2 sc1
	s_waitcnt lgkmcnt(0)
	s_waitcnt vmcnt(0)
	buffer_inv sc1
	v_mbcnt_lo_u32_b32 v1, s8, 0
	v_mbcnt_hi_u32_b32 v1, s9, v1
	v_cmp_eq_u32_e32 vcc, 0, v1
	s_and_saveexec_b64 s[10:11], vcc
	s_cbranch_execz .LBB0_394
	s_bcnt1_i32_b64 s3, s[8:9]
	v_mov_b32_e32 v2, 0x11083000
	v_mov_b32_e32 v3, s3
	global_atomic_add v2, v2, v3, s[4:5] offset:1024 sc0

.LBB0_408:
	s_or_b64 exec, exec, s[4:5]
	s_mov_b64 s[4:5], exec
	v_mbcnt_lo_u32_b32 v0, s4, 0
	v_mbcnt_hi_u32_b32 v0, s5, v0
	v_cmp_eq_u32_e32 vcc, 0, v0
	s_waitcnt vmcnt(0)
	s_and_saveexec_b64 s[8:9], vcc
	s_cbranch_execz .LBB0_410
	s_bcnt1_i32_b64 s3, s[4:5]
	v_mov_b32_e32 v0, 0x2000
	v_mov_b32_e32 v1, s3
.LBB0_410:
	s_or_b64 exec, exec, s[8:9]
	s_waitcnt vmcnt(0)

.LBB0_614:
	s_andn2_saveexec_b64 s[0:1], s[12:13]
	s_cbranch_execz .LBB0_634
	s_mov_b64 s[12:13], exec
	buffer_wbl2 sc1
	s_waitcnt lgkmcnt(0)
	s_waitcnt vmcnt(0)
	buffer_inv sc1
	v_mbcnt_lo_u32_b32 v1, s12, 0
	v_mbcnt_hi_u32_b32 v1, s13, v1
	v_cmp_eq_u32_e32 vcc, 0, v1
	s_and_saveexec_b64 s[14:15], vcc
	s_cbranch_execz .LBB0_617
	s_bcnt1_i32_b64 s0, s[12:13]
	v_mov_b32_e32 v2, s0
	global_atomic_add v2, v219, v2, s[8:9] offset:1024 sc0

.LBB0_631:
	s_or_b64 exec, exec, s[8:9]
	s_mov_b64 s[8:9], exec
	v_mbcnt_lo_u32_b32 v0, s8, 0
	v_mbcnt_hi_u32_b32 v0, s9, v0
	v_cmp_eq_u32_e32 vcc, 0, v0
	s_waitcnt vmcnt(0)
	s_and_saveexec_b64 s[12:13], vcc
	s_cbranch_execz .LBB0_633
	s_bcnt1_i32_b64 s0, s[8:9]
	v_mov_b32_e32 v0, s0
.LBB0_633:
	s_or_b64 exec, exec, s[12:13]
	s_waitcnt vmcnt(0)

.LBB0_722:
	s_andn2_saveexec_b64 s[0:1], s[12:13]
	s_cbranch_execz .LBB0_742
	s_mov_b64 s[12:13], exec
	buffer_wbl2 sc1
	s_waitcnt lgkmcnt(0)
	s_waitcnt vmcnt(0)
	v_mbcnt_lo_u32_b32 v1, s12, 0
	buffer_inv sc1
	v_mbcnt_hi_u32_b32 v1, s13, v1
	v_cmp_eq_u32_e32 vcc, 0, v1
	s_and_saveexec_b64 s[14:15], vcc
	s_cbranch_execz .LBB0_725
	s_bcnt1_i32_b64 s0, s[12:13]
	v_mov_b32_e32 v2, s0
	global_atomic_add v2, v219, v2, s[8:9] offset:1024 sc0

.LBB0_739:
	s_or_b64 exec, exec, s[8:9]
	s_mov_b64 s[8:9], exec
	v_mbcnt_lo_u32_b32 v0, s8, 0
	v_mbcnt_hi_u32_b32 v0, s9, v0
	v_cmp_eq_u32_e32 vcc, 0, v0
	s_waitcnt vmcnt(0)
	s_and_saveexec_b64 s[12:13], vcc
	s_cbranch_execz .LBB0_741
	s_bcnt1_i32_b64 s0, s[8:9]
	v_mov_b32_e32 v0, s0
.LBB0_741:
	s_or_b64 exec, exec, s[12:13]
	s_waitcnt vmcnt(0)

.LBB0_879:
	s_andn2_saveexec_b64 s[0:1], s[12:13]
	s_cbranch_execz .LBB0_899
	s_mov_b64 s[12:13], exec
	buffer_wbl2 sc1
	s_waitcnt lgkmcnt(0)
	s_waitcnt vmcnt(0)
	v_mbcnt_lo_u32_b32 v1, s12, 0
	v_mbcnt_hi_u32_b32 v1, s13, v1
	buffer_inv sc1
	v_cmp_eq_u32_e32 vcc, 0, v1
	s_and_saveexec_b64 s[14:15], vcc
	s_cbranch_execz .LBB0_882
	s_bcnt1_i32_b64 s0, s[12:13]
	v_mov_b32_e32 v2, s0
	global_atomic_add v2, v219, v2, s[8:9] offset:1024 sc0

.LBB0_896:
	s_or_b64 exec, exec, s[8:9]
	s_mov_b64 s[8:9], exec
	v_mbcnt_lo_u32_b32 v0, s8, 0
	v_mbcnt_hi_u32_b32 v0, s9, v0
	v_cmp_eq_u32_e32 vcc, 0, v0
	s_waitcnt vmcnt(0)
	s_and_saveexec_b64 s[12:13], vcc
	s_cbranch_execz .LBB0_898
	s_bcnt1_i32_b64 s0, s[8:9]
	v_mov_b32_e32 v0, s0
.LBB0_898:
	s_or_b64 exec, exec, s[12:13]
	s_waitcnt vmcnt(0)

.LBB0_949:
	s_andn2_saveexec_b64 s[0:1], s[12:13]
	s_cbranch_execz .LBB0_969
	s_mov_b64 s[12:13], exec
	buffer_wbl2 sc1
	s_waitcnt lgkmcnt(0)
	s_waitcnt vmcnt(0)
	v_mbcnt_lo_u32_b32 v1, s12, 0
	v_mbcnt_hi_u32_b32 v1, s13, v1
	v_cmp_eq_u32_e32 vcc, 0, v1
	buffer_inv sc1
	s_and_saveexec_b64 s[14:15], vcc
	s_cbranch_execz .LBB0_952
	s_bcnt1_i32_b64 s0, s[12:13]
	v_mov_b32_e32 v2, s0
	global_atomic_add v2, v219, v2, s[8:9] offset:1024 sc0

.LBB0_966:
	s_or_b64 exec, exec, s[8:9]
	s_mov_b64 s[8:9], exec
	v_mbcnt_lo_u32_b32 v0, s8, 0
	v_mbcnt_hi_u32_b32 v0, s9, v0
	v_cmp_eq_u32_e32 vcc, 0, v0
	s_waitcnt vmcnt(0)
	s_and_saveexec_b64 s[12:13], vcc
	s_cbranch_execz .LBB0_968
	s_bcnt1_i32_b64 s0, s[8:9]
	v_mov_b32_e32 v0, s0
.LBB0_968:
	s_or_b64 exec, exec, s[12:13]
	s_waitcnt vmcnt(0)

.LBB0_1033:
	s_or_b64 exec, exec, s[8:9]
	s_mov_b64 s[8:9], exec
	v_mbcnt_lo_u32_b32 v0, s8, 0
	v_mbcnt_hi_u32_b32 v0, s9, v0
	v_cmp_eq_u32_e32 vcc, 0, v0
	s_waitcnt vmcnt(0)
	s_and_saveexec_b64 s[12:13], vcc
	s_cbranch_execz .LBB0_1035
	s_bcnt1_i32_b64 s0, s[8:9]
	v_mov_b32_e32 v0, s0
.LBB0_1035:
	s_or_b64 exec, exec, s[12:13]
	s_waitcnt vmcnt(0)

.LBB0_1197:
	s_andn2_saveexec_b64 s[0:1], s[12:13]
	s_cbranch_execz .LBB0_1217
	s_mov_b64 s[12:13], exec
	buffer_wbl2 sc1
	s_waitcnt lgkmcnt(0)
	s_waitcnt vmcnt(0)
	v_mbcnt_lo_u32_b32 v1, s12, 0
	v_mbcnt_hi_u32_b32 v1, s13, v1
	v_cmp_eq_u32_e32 vcc, 0, v1
	s_and_saveexec_b64 s[14:15], vcc
	buffer_inv sc1
	s_cbranch_execz .LBB0_1200
	s_bcnt1_i32_b64 s0, s[12:13]
	v_mov_b32_e32 v2, s0
	global_atomic_add v2, v219, v2, s[8:9] offset:1024 sc0

.LBB0_1214:
	s_or_b64 exec, exec, s[8:9]
	s_mov_b64 s[8:9], exec
	v_mbcnt_lo_u32_b32 v0, s8, 0
	v_mbcnt_hi_u32_b32 v0, s9, v0
	v_cmp_eq_u32_e32 vcc, 0, v0
	s_waitcnt vmcnt(0)
	s_and_saveexec_b64 s[12:13], vcc
	s_cbranch_execz .LBB0_1216
	s_bcnt1_i32_b64 s0, s[8:9]
	v_mov_b32_e32 v0, s0
.LBB0_1216:
	s_or_b64 exec, exec, s[12:13]
	s_waitcnt vmcnt(0)

.LBB0_1289:
	s_andn2_saveexec_b64 s[0:1], s[16:17]
	s_cbranch_execz .LBB0_1309
	s_mov_b64 s[16:17], exec
	buffer_wbl2 sc1
	s_waitcnt lgkmcnt(0)
	s_waitcnt vmcnt(0)
	v_mbcnt_lo_u32_b32 v1, s16, 0
	v_mbcnt_hi_u32_b32 v1, s17, v1
	v_cmp_eq_u32_e32 vcc, 0, v1
	s_and_saveexec_b64 s[18:19], vcc
	s_cbranch_execz .LBB0_1292
	buffer_inv sc1
	s_bcnt1_i32_b64 s0, s[16:17]
	v_mov_b32_e32 v2, s0
	global_atomic_add v2, v219, v2, s[12:13] offset:1024 sc0

.LBB0_1639:
	s_mov_b64 s[12:13], exec
	buffer_wbl2 sc1
	s_waitcnt lgkmcnt(0)
	s_waitcnt vmcnt(0)
	v_mbcnt_lo_u32_b32 v1, s12, 0
	v_mbcnt_hi_u32_b32 v1, s13, v1
	v_cmp_eq_u32_e32 vcc, 0, v1
	s_and_saveexec_b64 s[14:15], vcc
	s_cbranch_execz .LBB0_1641
	buffer_inv sc1
	s_bcnt1_i32_b64 s0, s[12:13]
	v_mov_b32_e32 v2, s0
	global_atomic_add v2, v219, v2, s[8:9] offset:1024 sc0

.LBB0_1655:
	s_or_b64 exec, exec, s[8:9]
	s_mov_b64 s[8:9], exec
	v_mbcnt_lo_u32_b32 v0, s8, 0
	v_mbcnt_hi_u32_b32 v0, s9, v0
	v_cmp_eq_u32_e32 vcc, 0, v0
	s_waitcnt vmcnt(0)
	s_and_saveexec_b64 s[12:13], vcc
	s_cbranch_execnz .LBB0_1656
	s_getpc_b64 s[98:99]
